# prologue: weight-transpose items rotated by 512 waves per matrix so the 12 small matrices no longer all land on waves 0..255
# speedup vs baseline: 1.0048x; 1.0048x over previous
; __global__ void __launch_bounds__(512) fwd_megakernel(KArgs a) {
;     ...
;         for (int mi = 0; mi < 20; ++mi) {
;             const float* W; const float* gain; bf16* WT; int K, N;
;             if (mi < 8) { const int j = mi >> 2, kind = mi & 3; unsigned char* wb = ws + WS_WMLA + j * W_MLA_SZ;
;                 if (kind == 0) { W = a.mla_w_in + (size_t)j * 1024 * 704; gain = a.attn_norm + (2 * j) * 1024; K = 1024; N = 704; WT = (bf16*)(wb + W_MLA_IN); }
;                 else if (kind == 1) { W = a.mla_w_uq + (size_t)j * 384 * 1536; gain = a.mla_qa + j * 384; K = 384; N = 1536; WT = (bf16*)(wb + W_MLA_UQ); }
;                 else if (kind == 2) { W = a.mla_w_ukv + (size_t)j * 256 * 2048; gain = a.mla_kva + j * 256; K = 256; N = 2048; WT = (bf16*)(wb + W_MLA_UKV); }
;                 else { W = a.mla_w_o + (size_t)j * 1024 * 1024; gain = nullptr; K = 1024; N = 1024; WT = (bf16*)(wb + W_MLA_O); } }
;             else if (mi < 12) { const int j = (mi - 8) >> 1, kind = (mi - 8) & 1; unsigned char* wb = ws + WS_WMOBA + j * W_MOBA_SZ;
;                 if (kind == 0) { W = a.moba_w_qkv + (size_t)j * 1024 * 3072; gain = a.attn_norm + (2 * j + 1) * 1024; K = 1024; N = 3072; WT = (bf16*)(wb + W_MOBA_QKV); }
;                 else { W = a.moba_w_o + (size_t)j * 1024 * 1024; gain = nullptr; K = 1024; N = 1024; WT = (bf16*)(wb + W_MOBA_O); } }
;             else { const int i = (mi - 12) >> 1, kind = (mi - 12) & 1; unsigned char* wb = ws + WS_WMLP + i * W_MLP_SZ;
;                 if (kind == 0) { W = a.mlp_w_in + (size_t)i * 1024 * 4096; gain = a.mlp_norm + i * 1024; K = 1024; N = 4096; WT = (bf16*)(wb + W_MLP_IN); }
;                 else { W = a.mlp_w_out + (size_t)i * 4096 * 1024; gain = nullptr; K = 4096; N = 1024; WT = (bf16*)(wb + W_MLP_OUT); } }
;             const int nitems = (K / 64) * (N / 32);
;             for (int it = gw; it < nitems; it += NGW) transpose_item(W, gain, K, N, WT, scr, it, lane);
;         }
.LBB0_8:
	s_addk_i32 s70, 0x200
	s_and_b32 s70, s70, 0x7ff
	s_add_i32 s23, s23, 1
	s_cmp_eq_u32 s23, 20
	s_cbranch_scc1 .LBB0_70
